# attn loop single barrier per KV tile + all exps in PV gaps + generated tail; gains-max unrolled; scan wave0 counted vmcnt
# speedup vs baseline: 1.0332x; 1.0052x over previous
; __device__ __forceinline__ unsigned cvt_pk(float lo, float hi) { unsigned r; asm volatile("v_cvt_pk_bf16_f32 %0, %1, %2" : "=v"(r) : "v"(lo), "v"(hi)); return r; }
; template <int SPLIT> __device__ __forceinline__ void scan_item(const Params& p, unsigned char* smem, const int item, const int vh) {
;     ...
;     unsigned char* KP = smem; unsigned char* VT = smem + 32768; unsigned char* KT = smem + 65536; unsigned char* CS = smem + 98304;
;     float* g_s = (float*)(smem + 131072); float* a_s = g_s + 128; float* M_s = a_s + 128; float* n_s = M_s + 128; float* sc = n_s + 128;
;     {
;         int b, h, dir, T, rb;
;         if (item < 64) { b = item >> 3; h = (item >> 1) & 3; dir = item & 1; T = 4096; rb = b * 4096; }
;         else { const int it = item - 64; b = it >> 3; h = (it >> 1) & 3; dir = it & 1; T = 2048; rb = NPROMPT + b * 2048; }
;         const int nc = T >> 7;
;         const int rfirst = dir ? rb + T - 1 : rb, rstep = dir ? -1 : 1;
;         const float bgi = p.bgi[dir * 4 + h], bgf = p.bgf[dir * 4 + h];
;         for (int idx = tid; idx < 2048; idx += 512) *(u32x4*)(CS + idx * 16) = (u32x4){0u, 0u, 0u, 0u};
;         if (tid < 128) n_s[tid] = 0.f;
;         float m_run = -1e30f;
;         f32x4 Cacc[NBV];
; #pragma unroll
;         for (int nb = 0; nb < NBV; ++nb) Cacc[nb] = (f32x4){0.f, 0.f, 0.f, 0.f};
;         const int vblk = SPLIT ? 4 * vh + (wid & 3) : wid, kh = SPLIT ? (wid >> 2) : 0;
;         const int sp = tid & 31, ch = tid >> 5;
;         u32x4 kreg[4], vreg[4]; bf16x8 qf[4];
;     ...
;             const int l = wid * 16 + li;
;             const float Ml = M_s[l], gl = g_s[l];
;             f32x4 acc[8];
; #pragma unroll
;             for (int nb = 0; nb < 8; ++nb) acc[nb] = (f32x4){0.f, 0.f, 0.f, 0.f};
;             mm16<8>(acc, KP, qf, lane);
;             __builtin_amdgcn_sched_barrier(0);
;             float rs = 0.f; u32x2 pp[8];
;             const float rowf = __expf(fminf(sc[1] - Ml, 80.f));
; #pragma unroll
;             for (int nb = 0; nb < 8; ++nb) { float pv[4];
; #pragma unroll
;                 for (int jj = 0; jj < 4; ++jj) { const int s = nb * 16 + kq * 4 + jj; pv[jj] = (s <= l) ? acc[nb][jj] * rowf : 0.f; rs += pv[jj]; }
;                 pp[nb].x = cvt_pk(pv[0], pv[1]); pp[nb].y = cvt_pk(pv[2], pv[3]); }
.LBB0_288:
	s_or_b64 exec, exec, s[6:7]
	s_add_i32 s0, 0, 0x20200
	v_lshlrev_b32_e32 v52, 2, v52
	v_lshl_add_u32 v116, v113, 2, s0
	s_add_i32 s4, 0, 0x20000
	v_add_u32_e32 v118, s0, v52
	s_add_i32 s0, 0, 0x20400
	v_add_u32_e32 v117, s4, v52
	v_add_u32_e32 v119, s0, v52
	v_lshlrev_b32_e32 v52, 3, v54
	v_cmp_eq_u32_e64 s[6:7], 0, v55
	v_and_b32_e32 v52, 8, v52
	s_add_i32 s89, 0, 0x10000
	v_lshlrev_b32_e32 v65, 2, v114
	v_writelane_b32 v254, s6, 56
	v_add_u32_e32 v120, s89, v52
	v_add_u32_e32 v121, 0, v52
	v_add_u32_e32 v122, s0, v65
	v_xor_b32_e32 v52, v61, v57
	s_lshl_b32 s0, s8, 1
	v_writelane_b32 v254, s7, 57
	v_lshlrev_b32_e32 v124, 4, v52
	v_bitop3_b32 v52, v61, v57, 4 bitop3:0x36
	s_add_u32 s6, s76, s0
	v_add_u32_e32 v123, s4, v65
	v_lshlrev_b32_e32 v126, 4, v52
	v_bitop3_b32 v52, v61, v57, 8 bitop3:0x36
	s_addc_u32 s7, s77, 0
	s_lshl_b32 s4, s37, 10
	v_lshlrev_b32_e32 v128, 4, v52
	v_bitop3_b32 v52, v61, v57, 12 bitop3:0x36
	s_add_u32 s4, s78, s4
	v_lshlrev_b32_e32 v130, 4, v52
	v_lshlrev_b32_e32 v52, 1, v50
	v_mov_b32_e32 v53, v94
	s_addc_u32 s5, s79, 0
	v_lshl_add_u64 v[104:105], s[6:7], 0, v[52:53]
	s_add_u32 s6, s4, s0
	v_or_b32_e32 v62, 1, v113
	v_or_b32_e32 v63, 2, v113
	v_or_b32_e32 v64, 3, v113
	v_lshrrev_b32_e32 v54, 1, v60
	v_lshlrev_b32_e32 v69, 8, v114
	v_and_b32_e32 v70, 8, v50
	s_addc_u32 s7, s5, 0
	s_add_i32 s4, 0, 0x20600
	s_add_i32 s92, 0, 0x18000
	v_lshrrev_b32_e32 v68, 5, v55
	v_add3_u32 v132, 0, v69, v70
	v_lshl_add_u64 v[106:107], s[6:7], 0, v[50:51]
	v_add_u32_e32 v133, s89, v69
	v_add_u32_e32 v134, s4, v65
	v_add3_u32 v135, s92, v69, v70
	v_cmp_gt_u32_e64 s[8:9], 16, v55
	v_lshlrev_b32_e32 v50, 10, v60
	v_bitop3_b32 v51, v113, v59, 12 bitop3:0x6c
	v_lshlrev_b32_e32 v55, 8, v62
	v_bitop3_b32 v60, v62, v59, 13 bitop3:0x6c
	v_lshlrev_b32_e32 v62, 8, v63
	v_bitop3_b32 v63, v63, v59, 14 bitop3:0x6c
	v_lshlrev_b32_e32 v65, 8, v64
	v_bitop3_b32 v64, v64, v59, 15 bitop3:0x6c
	v_or_b32_e32 v69, 1, v48
	v_lshlrev_b32_e32 v59, 11, v59
	v_bitop3_b32 v70, v48, v54, 8 bitop3:0x6c
	v_lshl_or_b32 v136, v70, 4, v59
	v_lshlrev_b32_e32 v59, 8, v69
	v_bitop3_b32 v69, v69, v54, 9 bitop3:0x6c
	v_lshl_or_b32 v137, v69, 4, v59
	v_or_b32_e32 v59, 2, v48
	v_or_b32_e32 v69, 3, v48
	v_lshlrev_b32_e32 v70, 8, v59
	v_bitop3_b32 v59, v59, v54, 10 bitop3:0x6c
	v_lshl_or_b32 v138, v59, 4, v70
	v_lshlrev_b32_e32 v59, 8, v69
	v_bitop3_b32 v69, v69, v54, 11 bitop3:0x6c
	v_lshl_or_b32 v139, v69, 4, v59
	v_or_b32_e32 v59, 4, v48
	v_or_b32_e32 v69, 5, v48
	v_lshlrev_b32_e32 v70, 8, v59
	v_bitop3_b32 v59, v59, v54, 12 bitop3:0x6c
	v_lshl_or_b32 v140, v59, 4, v70
	v_lshlrev_b32_e32 v59, 8, v69
	v_bitop3_b32 v69, v69, v54, 13 bitop3:0x6c
	v_lshl_or_b32 v141, v69, 4, v59
	v_or_b32_e32 v59, 6, v48
	v_or_b32_e32 v69, 7, v48
	v_lshlrev_b32_e32 v70, 8, v59
	v_bitop3_b32 v59, v59, v54, 14 bitop3:0x6c
	v_lshlrev_b32_e32 v67, 2, v61
	v_lshl_or_b32 v142, v59, 4, v70
	v_lshlrev_b32_e32 v59, 8, v69
	v_bitop3_b32 v54, v69, v54, 15 bitop3:0x6c
	v_lshl_or_b32 v143, v54, 4, v59
	v_or_b32_e32 v54, 2, v67
	v_cmp_gt_i32_e64 s[14:15], v54, v114
	v_or_b32_e32 v54, 3, v67
	v_cmp_gt_i32_e64 s[16:17], v54, v114
	v_or_b32_e32 v54, 16, v67
	v_cmp_gt_i32_e64 s[18:19], v54, v114
	v_or_b32_e32 v54, 17, v67
	v_cmp_gt_i32_e64 s[20:21], v54, v114
	v_or_b32_e32 v54, 18, v67
	v_cmp_gt_i32_e64 s[22:23], v54, v114
	v_or_b32_e32 v54, 19, v67
	v_cmp_gt_i32_e64 s[24:25], v54, v114
	v_or_b32_e32 v54, 32, v67
	v_cmp_gt_i32_e64 s[26:27], v54, v114
	v_or_b32_e32 v54, 33, v67
	v_cmp_gt_i32_e64 s[28:29], v54, v114
	v_or_b32_e32 v54, 34, v67
	v_cmp_gt_i32_e64 s[30:31], v54, v114
	v_or_b32_e32 v54, 35, v67
	v_cmp_gt_i32_e64 s[34:35], v54, v114
	v_or_b32_e32 v54, 48, v67
	v_writelane_b32 v254, s37, 58
	v_cmp_gt_i32_e64 s[36:37], v54, v114
	v_or_b32_e32 v54, 49, v67
	v_cmp_gt_i32_e64 s[38:39], v54, v114
; #define SCAN_LOAD(j) do { \
;         _Pragma("unroll") for (int i = 0; i < 4; ++i) { const size_t r = (size_t)(rfirst + rstep * ((j) * 128 + sp * 4 + i)); \
;             kreg[i] = *(const u32x4*)(K0 + r * 512 + h * 128 + ch * 8); vreg[i] = *(const u32x4*)(P0 + r * LDP + 1536 + h * 128 + ch * 8); } \
;         } while (0)
; #define Q_LOAD(j) do { const size_t r = (size_t)(rfirst + rstep * ((j) * 128 + wid * 16 + li)); \
;           _Pragma("unroll") for (int ks = 0; ks < 4; ++ks) qf[ks] = *(const bf16x8*)(Q0 + r * 512 + h * 128 + ks * 32 + kq * 8); } while (0)
; #define GATE_LOAD(j) do { pg = *(const float2*)(scr + (j) * 384 + 2 * lane); pa = *(const float2*)(scr + (j) * 384 + 128 + 2 * lane); \
;         ppm = *(const float2*)(scr + (j) * 384 + 256 + 2 * lane); pG = scr[32 * 384 + (j)]; pPM = scr[32 * 384 + 32 + (j)]; } while (0)
; template <int SPLIT> __device__ __forceinline__ void scan_item(const Params& p, unsigned char* smem, const int item, const int vh) {
;     ...
;         float m_run = -1e30f;
;         f32x4 Cacc[NBV];
; #pragma unroll
;         for (int nb = 0; nb < NBV; ++nb) Cacc[nb] = (f32x4){0.f, 0.f, 0.f, 0.f};
;         const int vblk = SPLIT ? 4 * vh + (wid & 3) : wid, kh = SPLIT ? (wid >> 2) : 0;
;         const int sp = tid & 31, ch = tid >> 5;
;         u32x4 kreg[4], vreg[4]; bf16x8 qf[4];
;     ...
;         float2 pg = make_float2(0.f, 0.f), pa = pg, ppm = pg; float pG = 0.f, pPM = 0.f;
;         SCAN_LOAD(0); Q_LOAD(0);
;         if (wid == 0) GATE_LOAD(0);
;         for (int j = 0; j < nc; ++j) {
	v_or_b32_e32 v54, 50, v67
	v_cmp_gt_i32_e64 s[40:41], v54, v114
	v_or_b32_e32 v54, 51, v67
	v_cmp_gt_i32_e64 s[42:43], v54, v114
	v_or_b32_e32 v54, 64, v67
	v_cmp_gt_i32_e64 s[44:45], v54, v114
	v_or_b32_e32 v54, 0x41, v67
	v_cmp_gt_i32_e64 s[46:47], v54, v114
	v_or_b32_e32 v54, 0x42, v67
	v_cmp_gt_i32_e64 s[48:49], v54, v114
	v_or_b32_e32 v54, 0x43, v67
	v_cmp_gt_i32_e64 s[50:51], v54, v114
	v_or_b32_e32 v54, 0x50, v67
	v_cmp_gt_i32_e64 s[52:53], v54, v114
	v_or_b32_e32 v54, 0x51, v67
	v_cmp_gt_i32_e64 s[54:55], v54, v114
	v_or_b32_e32 v54, 0x52, v67
	v_cmp_gt_i32_e64 s[56:57], v54, v114
	v_or_b32_e32 v54, 0x53, v67
	v_cmp_gt_i32_e64 s[58:59], v54, v114
	v_or_b32_e32 v54, 0x60, v67
	v_cmp_gt_i32_e64 s[60:61], v54, v114
	v_or_b32_e32 v54, 0x61, v67
	v_cmp_gt_i32_e64 s[62:63], v54, v114
	v_or_b32_e32 v54, 0x62, v67
	v_cmp_gt_i32_e64 s[64:65], v54, v114
	v_or_b32_e32 v54, 0x63, v67
	v_cmp_gt_i32_e64 s[66:67], v54, v114
	v_or_b32_e32 v54, 0x70, v67
	v_cmp_gt_i32_e64 s[68:69], v54, v114
	v_or_b32_e32 v54, 0x71, v67
	v_cmp_gt_i32_e64 s[70:71], v54, v114
	v_or_b32_e32 v54, 0x72, v67
	v_cmp_gt_i32_e64 s[72:73], v54, v114
	v_or_b32_e32 v54, 0x73, v67
	v_cmp_gt_i32_e64 s[74:75], v54, v114
	v_xor_b32_e32 v54, v68, v57
	v_lshlrev_b32_e32 v144, 4, v54
	v_bitop3_b32 v54, v68, v57, 2 bitop3:0x36
	v_lshlrev_b32_e32 v145, 4, v54
	v_bitop3_b32 v54, v68, v57, 4 bitop3:0x36
	v_lshlrev_b32_e32 v146, 4, v54
	v_bitop3_b32 v54, v68, v57, 6 bitop3:0x36
	v_lshlrev_b32_e32 v147, 4, v54
	v_bitop3_b32 v54, v68, v57, 8 bitop3:0x36
	s_add_u32 s6, s78, s0
	v_lshlrev_b32_e32 v66, 8, v57
	v_lshlrev_b32_e32 v61, 5, v61
	v_lshlrev_b32_e32 v148, 4, v54
	v_bitop3_b32 v54, v68, v57, 10 bitop3:0x36
	s_addc_u32 s7, s79, 0
	v_lshl_or_b32 v52, v56, 12, v66
	v_lshlrev_b32_e32 v149, 4, v54
	v_bitop3_b32 v54, v68, v57, 12 bitop3:0x36
	v_lshl_add_u64 v[108:109], v[48:49], 1, s[6:7]
	v_add_u32_e32 v48, 0, v61
	v_or_b32_e32 v125, v124, v66
	v_or_b32_e32 v127, v126, v66
	v_or_b32_e32 v129, v128, v66
	v_or_b32_e32 v131, v130, v66
	v_or_b32_e32 v53, v124, v52
	v_or_b32_e32 v56, v126, v52
	v_or_b32_e32 v66, v128, v52
	v_or_b32_e32 v52, v130, v52
	v_lshl_add_u32 v51, v51, 4, 0
	v_lshl_add_u32 v60, v60, 4, 0
	v_lshl_add_u32 v63, v63, 4, 0
	v_lshl_add_u32 v64, v64, 4, 0
	v_lshlrev_b32_e32 v150, 4, v54
	v_bitop3_b32 v54, v68, v57, 14 bitop3:0x36
	s_add_i32 s87, s87, s86
	v_add_u32_e32 v158, 0x20600, v48
	v_mbcnt_lo_u32_b32 v48, -1, 0
	v_cmp_gt_i32_e64 s[10:11], v67, v114
	v_cmp_lt_i32_e64 s[12:13], v67, v114
	v_lshlrev_b32_e32 v151, 4, v54
	v_add_u32_e32 v152, s87, v58
	s_lshl_b32 s93, s3, 7
	v_mov_b32_e32 v110, 0xf149f2ca
	s_mov_b32 s95, -16
	s_add_i32 s94, 0, 0x20800
	v_mov_b32_e32 v153, 0xc000
	s_mov_b32 s90, 0xffff0000
	v_add_u32_e32 v154, v51, v50
	v_add_u32_e32 v155, v60, v55
	v_add_u32_e32 v156, v63, v62
	v_add_u32_e32 v157, v64, v65
	s_mov_b32 s91, 0xffff
	s_add_i32 s6, 0, 0x20804
	v_add_u32_e32 v159, 0, v53
	v_add_u32_e32 v160, 0, v56
	v_add_u32_e32 v161, 0, v66
	v_add_u32_e32 v162, 0, v52
	v_mbcnt_hi_u32_b32 v163, -1, v48
	v_mov_b32_e32 v60, 0
	v_mov_b32_e32 v61, v94
	v_mov_b32_e32 v62, v94
	v_mov_b32_e32 v63, v94
	v_mov_b32_e32 v52, 0
	v_mov_b32_e32 v53, v94
	v_mov_b32_e32 v54, v94
	v_mov_b32_e32 v55, v94
	v_mov_b32_e32 v48, 0
	v_mov_b32_e32 v49, v94
	v_mov_b32_e32 v50, v94
	v_mov_b32_e32 v51, v94
	v_mov_b32_e32 v56, 0
	v_mov_b32_e32 v57, v94
	v_mov_b32_e32 v58, v94
	v_mov_b32_e32 v59, v94
	v_mov_b32_e32 v64, 0
	v_mov_b32_e32 v65, v94
	v_mov_b32_e32 v66, v94
	v_mov_b32_e32 v67, v94
	v_mov_b32_e32 v68, 0
	v_mov_b32_e32 v69, v94
	v_mov_b32_e32 v70, v94
	v_mov_b32_e32 v71, v94
	v_mov_b32_e32 v72, 0
	v_mov_b32_e32 v73, v94
	v_mov_b32_e32 v74, v94
	v_mov_b32_e32 v75, v94
	v_mov_b32_e32 v76, 0
	v_mov_b32_e32 v77, v94
	v_mov_b32_e32 v78, v94
	v_mov_b32_e32 v79, v94
	s_waitcnt vmcnt(0)
	s_branch .LBB0_290

; #define GATE_LOAD(j) do { pg = *(const float2*)(scr + (j) * 384 + 2 * lane); pa = *(const float2*)(scr + (j) * 384 + 128 + 2 * lane); \
;         ppm = *(const float2*)(scr + (j) * 384 + 256 + 2 * lane); pG = scr[32 * 384 + (j)]; pPM = scr[32 * 384 + 32 + (j)]; } while (0)
; template <int SPLIT> __device__ __forceinline__ void scan_item(const Params& p, unsigned char* smem, const int item, const int vh) {
;     ...
;             if (wid == 0) {
;                 const float M127 = fmaxf(m_run, pPM);
;                 g_s[2 * lane] = pg.x; g_s[2 * lane + 1] = pg.y; a_s[2 * lane] = pa.x; a_s[2 * lane + 1] = pa.y;
;                 M_s[2 * lane] = fmaxf(m_run, ppm.x); M_s[2 * lane + 1] = fmaxf(m_run, ppm.y);
;                 if (lane == 0) { sc[0] = m_run; sc[1] = M127; }
;                 m_run = pG + M127;
;                 GATE_LOAD(jn);
;             }
.LBB0_290:
	s_add_i32 s0, s95, 17
	s_cmp_lg_u32 s95, -1
	v_readlane_b32 s4, v254, 54
	s_cselect_b32 vcc_lo, s0, 15
	v_readlane_b32 s5, v254, 55
	s_and_saveexec_b64 s[86:87], s[4:5]
	s_cbranch_execz .LBB0_294
	s_waitcnt vmcnt(20)
	v_max_f32_e32 v80, v111, v111
	s_waitcnt lgkmcnt(6)
	v_max_f32_e32 v81, v110, v110
	v_max_f32_e32 v111, v81, v80
	v_max_f32_e32 v80, v98, v98
	v_max_f32_e32 v82, v99, v99
	v_max_f32_e32 v80, v81, v80
	v_max_f32_e32 v81, v81, v82
	ds_write_b64 v117, v[100:101]
	ds_write_b64 v118, v[102:103]
	ds_write_b64 v119, v[80:81]
	s_mov_b64 s[96:97], exec
	v_readlane_b32 s4, v254, 56
	v_readlane_b32 s5, v254, 57
	s_and_b64 s[4:5], s[96:97], s[4:5]
	s_mov_b64 exec, s[4:5]
	v_mov_b32_e32 v80, s94
	ds_write_b64 v80, v[110:111]
	s_or_b64 exec, exec, s[96:97]
	s_mov_b32 vcc_hi, s1
	s_mul_i32 s0, vcc_lo, 0x180
	s_lshl_b64 s[4:5], vcc, 2
	v_lshl_add_u64 v[80:81], s[0:1], 2, v[96:97]
	s_add_u32 s4, s84, s4
	v_add_f32_e32 v110, v115, v111
	s_addc_u32 s5, s85, s5
	global_load_dwordx2 v[100:101], v[80:81], off
	global_load_dwordx2 v[102:103], v[80:81], off offset:512
	global_load_dwordx2 v[98:99], v[80:81], off offset:1024
	global_load_dword v115, v153, s[4:5]
	global_load_dword v111, v153, s[4:5] offset:128

; __device__ __forceinline__ unsigned cvt_pk(float lo, float hi) { unsigned r; asm volatile("v_cvt_pk_bf16_f32 %0, %1, %2" : "=v"(r) : "v"(lo), "v"(hi)); return r; }
; template <int SPLIT> __device__ __forceinline__ void scan_item(const Params& p, unsigned char* smem, const int item, const int vh) {
;     ...
;     unsigned char* KP = smem; unsigned char* VT = smem + 32768; unsigned char* KT = smem + 65536; unsigned char* CS = smem + 98304;
;     float* g_s = (float*)(smem + 131072); float* a_s = g_s + 128; float* M_s = a_s + 128; float* n_s = M_s + 128; float* sc = n_s + 128;
;     {
;         int b, h, dir, T, rb;
;         if (item < 64) { b = item >> 3; h = (item >> 1) & 3; dir = item & 1; T = 4096; rb = b * 4096; }
;         else { const int it = item - 64; b = it >> 3; h = (it >> 1) & 3; dir = it & 1; T = 2048; rb = NPROMPT + b * 2048; }
;         const int nc = T >> 7;
;         const int rfirst = dir ? rb + T - 1 : rb, rstep = dir ? -1 : 1;
;         const float bgi = p.bgi[dir * 4 + h], bgf = p.bgf[dir * 4 + h];
;         for (int idx = tid; idx < 2048; idx += 512) *(u32x4*)(CS + idx * 16) = (u32x4){0u, 0u, 0u, 0u};
;         if (tid < 128) n_s[tid] = 0.f;
;         float m_run = -1e30f;
;         f32x4 Cacc[NBV];
; #pragma unroll
;         for (int nb = 0; nb < NBV; ++nb) Cacc[nb] = (f32x4){0.f, 0.f, 0.f, 0.f};
;         const int vblk = SPLIT ? 4 * vh + (wid & 3) : wid, kh = SPLIT ? (wid >> 2) : 0;
;         const int sp = tid & 31, ch = tid >> 5;
;         u32x4 kreg[4], vreg[4]; bf16x8 qf[4];
;     ...
;             const int l = wid * 16 + li;
;             const float Ml = M_s[l], gl = g_s[l];
;             f32x4 acc[8];
; #pragma unroll
;             for (int nb = 0; nb < 8; ++nb) acc[nb] = (f32x4){0.f, 0.f, 0.f, 0.f};
;             mm16<8>(acc, KP, qf, lane);
;             __builtin_amdgcn_sched_barrier(0);
;             float rs = 0.f; u32x2 pp[8];
;             const float rowf = __expf(fminf(sc[1] - Ml, 80.f));
; #pragma unroll
;             for (int nb = 0; nb < 8; ++nb) { float pv[4];
; #pragma unroll
;                 for (int jj = 0; jj < 4; ++jj) { const int s = nb * 16 + kq * 4 + jj; pv[jj] = (s <= l) ? acc[nb][jj] * rowf : 0.f; rs += pv[jj]; }
;                 pp[nb].x = cvt_pk(pv[0], pv[1]); pp[nb].y = cvt_pk(pv[2], pv[3]); }
.LBB0_310:
	s_or_b64 exec, exec, s[6:7]
	s_add_i32 s5, 0, 0x20200
	v_lshlrev_b32_e32 v52, 2, v52
	v_lshl_add_u32 v98, v85, 2, s5
	s_add_i32 s6, 0, 0x20000
	v_add_u32_e32 v100, s5, v52
	s_add_i32 s5, 0, 0x20400
	v_add_u32_e32 v99, s6, v52
	v_add_u32_e32 v101, s5, v52
	v_lshlrev_b32_e32 v52, 3, v54
	v_and_b32_e32 v52, 8, v52
	s_add_i32 s9, 0, 0x10000
	v_add_u32_e32 v102, s9, v52
	v_add_u32_e32 v103, 0, v52
	v_xor_b32_e32 v52, v61, v57
	s_lshl_b32 s0, s37, 14
	s_add_i32 s4, 0, 0x18000
	v_lshlrev_b32_e32 v81, 2, v96
	v_lshlrev_b32_e32 v106, 4, v52
	v_bitop3_b32 v52, v61, v57, 4 bitop3:0x36
	s_add_i32 s89, s4, s0
	s_add_i32 s90, s0, 0
	v_add_u32_e32 v104, s5, v81
	v_lshlrev_b32_e32 v108, 4, v52
	v_bitop3_b32 v52, v61, v57, 8 bitop3:0x36
	s_lshl_b32 s5, s8, 1
	v_add_u32_e32 v105, s6, v81
	v_lshlrev_b32_e32 v110, 4, v52
	v_bitop3_b32 v52, v61, v57, 12 bitop3:0x36
	s_add_u32 s6, s76, s5
	v_lshlrev_b32_e32 v112, 4, v52
	s_addc_u32 s7, s77, 0
	v_lshlrev_b32_e32 v52, 1, v50
	v_mov_b32_e32 v53, v66
	v_lshl_add_u64 v[76:77], s[6:7], 0, v[52:53]
	s_lshl_b32 s6, s24, 10
	s_add_u32 s6, s78, s6
	s_addc_u32 s7, s79, 0
	s_add_u32 s6, s6, s5
	s_addc_u32 s7, s7, 0
	s_lshl_b32 s8, s37, 7
	s_add_u32 s6, s6, s8
	v_lshlrev_b32_e32 v52, 12, v56
	s_addc_u32 s7, s7, 0
	v_and_b32_e32 v88, 8, v50
	v_lshl_add_u64 v[78:79], s[6:7], 0, v[50:51]
	v_and_b32_e32 v50, 0x3000, v52
	v_or_b32_e32 v62, 1, v85
	v_or_b32_e32 v63, 2, v85
	v_or_b32_e32 v67, 3, v85
	v_ashrrev_i32_e32 v80, 8, v54
	v_lshrrev_b32_e32 v54, 1, v60
	v_lshlrev_b32_e32 v87, 8, v96
	v_or_b32_e32 v50, s0, v50
	s_add_i32 s0, 0, 0x20600
	v_cmp_eq_u32_e64 s[10:11], 0, v55
	v_lshrrev_b32_e32 v86, 5, v55
	v_add3_u32 v89, 0, v87, v88
	v_lshl_add_u32 v120, v80, 14, s9
	v_add_u32_e32 v121, s9, v87
	v_add_u32_e32 v122, s0, v81
	v_lshlrev_b32_e32 v51, 3, v80
	v_cmp_gt_u32_e64 s[8:9], 16, v55
	v_lshlrev_b32_e32 v53, 10, v60
	v_bitop3_b32 v55, v85, v59, 12 bitop3:0x6c
	v_lshlrev_b32_e32 v56, 8, v62
	v_bitop3_b32 v60, v62, v59, 13 bitop3:0x6c
	v_lshlrev_b32_e32 v62, 8, v63
	v_bitop3_b32 v63, v63, v59, 14 bitop3:0x6c
	v_lshlrev_b32_e32 v87, 8, v67
	v_bitop3_b32 v67, v67, v59, 15 bitop3:0x6c
	v_or_b32_e32 v80, 1, v48
	v_lshlrev_b32_e32 v59, 11, v59
	v_bitop3_b32 v81, v48, v54, 8 bitop3:0x6c
	v_lshl_or_b32 v123, v81, 4, v59
	v_lshlrev_b32_e32 v59, 8, v80
	v_bitop3_b32 v80, v80, v54, 9 bitop3:0x6c
	v_lshl_or_b32 v124, v80, 4, v59
	v_or_b32_e32 v59, 2, v48
	v_or_b32_e32 v80, 3, v48
	v_lshlrev_b32_e32 v81, 8, v59
	v_bitop3_b32 v59, v59, v54, 10 bitop3:0x6c
	v_lshl_or_b32 v125, v59, 4, v81
	v_lshlrev_b32_e32 v59, 8, v80
	v_bitop3_b32 v80, v80, v54, 11 bitop3:0x6c
	v_lshl_or_b32 v126, v80, 4, v59
	v_or_b32_e32 v59, 4, v48
	v_or_b32_e32 v80, 5, v48
	v_lshlrev_b32_e32 v81, 8, v59
	v_bitop3_b32 v59, v59, v54, 12 bitop3:0x6c
	v_lshl_or_b32 v127, v59, 4, v81
	v_lshlrev_b32_e32 v59, 8, v80
	v_bitop3_b32 v80, v80, v54, 13 bitop3:0x6c
	v_lshl_or_b32 v128, v80, 4, v59
	v_or_b32_e32 v59, 6, v48
	v_or_b32_e32 v80, 7, v48
	v_lshlrev_b32_e32 v81, 8, v59
	v_bitop3_b32 v59, v59, v54, 14 bitop3:0x6c
	v_lshlrev_b32_e32 v84, 2, v61
	v_lshl_or_b32 v129, v59, 4, v81
	v_lshlrev_b32_e32 v59, 8, v80
	v_bitop3_b32 v54, v80, v54, 15 bitop3:0x6c
	v_lshl_or_b32 v130, v54, 4, v59
	v_or_b32_e32 v54, 2, v84
	v_cmp_gt_i32_e64 s[14:15], v54, v96
	v_or_b32_e32 v54, 3, v84
	v_cmp_gt_i32_e64 s[16:17], v54, v96
	v_or_b32_e32 v54, 16, v84
	v_cmp_gt_i32_e64 s[18:19], v54, v96
	v_or_b32_e32 v54, 17, v84
	v_cmp_gt_i32_e64 s[20:21], v54, v96
	v_or_b32_e32 v54, 18, v84
	v_cmp_gt_i32_e64 s[22:23], v54, v96
	v_or_b32_e32 v54, 19, v84
	v_cmp_gt_i32_e64 s[24:25], v54, v96
	v_or_b32_e32 v54, 32, v84
	v_cmp_gt_i32_e64 s[26:27], v54, v96
	v_or_b32_e32 v54, 33, v84
	v_cmp_gt_i32_e64 s[28:29], v54, v96
	v_or_b32_e32 v54, 34, v84
	v_cmp_gt_i32_e64 s[30:31], v54, v96
	v_or_b32_e32 v54, 35, v84
	v_cmp_gt_i32_e64 s[34:35], v54, v96
	v_or_b32_e32 v54, 48, v84
	v_cmp_gt_i32_e64 s[36:37], v54, v96
	v_or_b32_e32 v54, 49, v84
	v_cmp_gt_i32_e64 s[38:39], v54, v96
	v_or_b32_e32 v54, 50, v84
	v_cmp_gt_i32_e64 s[40:41], v54, v96
	v_or_b32_e32 v54, 51, v84
; #define SCAN_LOAD(j) do { \
;         _Pragma("unroll") for (int i = 0; i < 4; ++i) { const size_t r = (size_t)(rfirst + rstep * ((j) * 128 + sp * 4 + i)); \
;             kreg[i] = *(const u32x4*)(K0 + r * 512 + h * 128 + ch * 8); vreg[i] = *(const u32x4*)(P0 + r * LDP + 1536 + h * 128 + ch * 8); } \
;         } while (0)
; #define Q_LOAD(j) do { const size_t r = (size_t)(rfirst + rstep * ((j) * 128 + wid * 16 + li)); \
;           _Pragma("unroll") for (int ks = 0; ks < 4; ++ks) qf[ks] = *(const bf16x8*)(Q0 + r * 512 + h * 128 + ks * 32 + kq * 8); } while (0)
; #define GATE_LOAD(j) do { pg = *(const float2*)(scr + (j) * 384 + 2 * lane); pa = *(const float2*)(scr + (j) * 384 + 128 + 2 * lane); \
;         ppm = *(const float2*)(scr + (j) * 384 + 256 + 2 * lane); pG = scr[32 * 384 + (j)]; pPM = scr[32 * 384 + 32 + (j)]; } while (0)
; template <int SPLIT> __device__ __forceinline__ void scan_item(const Params& p, unsigned char* smem, const int item, const int vh) {
;     ...
;         float m_run = -1e30f;
;         f32x4 Cacc[NBV];
; #pragma unroll
;         for (int nb = 0; nb < NBV; ++nb) Cacc[nb] = (f32x4){0.f, 0.f, 0.f, 0.f};
;         const int vblk = SPLIT ? 4 * vh + (wid & 3) : wid, kh = SPLIT ? (wid >> 2) : 0;
;         const int sp = tid & 31, ch = tid >> 5;
;         u32x4 kreg[4], vreg[4]; bf16x8 qf[4];
;     ...
;         float2 pg = make_float2(0.f, 0.f), pa = pg, ppm = pg; float pG = 0.f, pPM = 0.f;
;         SCAN_LOAD(0); Q_LOAD(0);
;         if (wid == 0) GATE_LOAD(0);
;         for (int j = 0; j < nc; ++j) {
	v_cmp_gt_i32_e64 s[42:43], v54, v96
	v_or_b32_e32 v54, 64, v84
	v_cmp_gt_i32_e64 s[44:45], v54, v96
	v_or_b32_e32 v54, 0x41, v84
	v_cmp_gt_i32_e64 s[46:47], v54, v96
	v_or_b32_e32 v54, 0x42, v84
	v_cmp_gt_i32_e64 s[48:49], v54, v96
	v_or_b32_e32 v54, 0x43, v84
	v_cmp_gt_i32_e64 s[50:51], v54, v96
	v_or_b32_e32 v54, 0x50, v84
	v_cmp_gt_i32_e64 s[52:53], v54, v96
	v_or_b32_e32 v54, 0x51, v84
	v_cmp_gt_i32_e64 s[54:55], v54, v96
	v_or_b32_e32 v54, 0x52, v84
	v_cmp_gt_i32_e64 s[56:57], v54, v96
	v_or_b32_e32 v54, 0x53, v84
	v_cmp_gt_i32_e64 s[58:59], v54, v96
	v_or_b32_e32 v54, 0x60, v84
	v_cmp_gt_i32_e64 s[60:61], v54, v96
	v_or_b32_e32 v54, 0x61, v84
	v_cmp_gt_i32_e64 s[62:63], v54, v96
	v_or_b32_e32 v54, 0x62, v84
	v_cmp_gt_i32_e64 s[64:65], v54, v96
	v_or_b32_e32 v54, 0x63, v84
	v_cmp_gt_i32_e64 s[66:67], v54, v96
	v_or_b32_e32 v54, 0x70, v84
	v_cmp_gt_i32_e64 s[68:69], v54, v96
	v_or_b32_e32 v54, 0x71, v84
	v_writelane_b32 v254, s10, 56
	v_lshlrev_b32_e32 v82, 8, v57
	v_cmp_gt_i32_e64 s[70:71], v54, v96
	v_or_b32_e32 v54, 0x72, v84
	v_bitop3_b32 v80, v86, v57, 4 bitop3:0x36
	v_writelane_b32 v254, s11, 57
	v_or_b32_e32 v119, v50, v82
	v_add_u32_e32 v50, s4, v50
	v_cmp_gt_i32_e64 s[10:11], v84, v96
	v_cmp_lt_i32_e64 s[12:13], v84, v96
	v_cmp_gt_i32_e64 s[72:73], v54, v96
	v_or_b32_e32 v54, 0x73, v84
	v_lshlrev_b32_e32 v84, 4, v80
	v_bitop3_b32 v80, v86, v57, 6 bitop3:0x36
	v_add3_u32 v50, v50, v82, v88
	v_lshlrev_b32_e32 v88, 4, v80
	v_bitop3_b32 v80, v86, v57, 8 bitop3:0x36
	v_lshlrev_b32_e32 v90, 4, v80
	v_bitop3_b32 v80, v86, v57, 10 bitop3:0x36
	v_lshlrev_b32_e32 v91, 4, v80
	v_bitop3_b32 v80, v86, v57, 12 bitop3:0x36
	v_or_b32_e32 v114, v82, v52
	v_or_b32_e32 v52, v51, v86
	v_lshlrev_b32_e32 v92, 4, v80
	v_bitop3_b32 v80, v86, v57, 14 bitop3:0x36
	v_lshlrev_b32_e32 v93, 4, v80
	v_bitop3_b32 v80, v52, v57, 2 bitop3:0x36
	s_add_u32 s6, s78, s5
	v_lshlrev_b32_e32 v61, 5, v61
	v_cmp_gt_i32_e64 s[74:75], v54, v96
	v_xor_b32_e32 v54, v86, v57
	v_bitop3_b32 v59, v86, v57, 2 bitop3:0x36
	v_bitop3_b32 v51, v51, v57, v86 bitop3:0x36
	v_lshlrev_b32_e32 v86, 4, v80
	v_bitop3_b32 v80, v52, v57, 4 bitop3:0x36
	s_addc_u32 s7, s79, 0
	v_lshlrev_b32_e32 v94, 4, v80
	v_bitop3_b32 v52, v52, v57, 6 bitop3:0x36
	v_lshl_add_u64 v[80:81], v[48:49], 1, s[6:7]
	v_add_u32_e32 v48, 0, v61
	v_lshl_add_u32 v55, v55, 4, 0
	v_lshl_add_u32 v60, v60, 4, 0
	v_lshl_add_u32 v63, v63, 4, 0
	v_lshl_add_u32 v67, v67, 4, 0
	v_lshlrev_b32_e32 v54, 4, v54
	v_lshlrev_b32_e32 v59, 4, v59
	v_lshlrev_b32_e32 v51, 4, v51
	v_lshlrev_b32_e32 v52, 4, v52
	s_add_i32 s86, s86, s87
	v_add_u32_e32 v137, 0x20600, v48
	v_mbcnt_lo_u32_b32 v48, -1, 0
	v_or_b32_e32 v107, v106, v82
	v_or_b32_e32 v109, v108, v82
	v_or_b32_e32 v111, v110, v82
	v_or_b32_e32 v113, v112, v82
	v_add_u32_e32 v115, 0, v106
	v_add_u32_e32 v116, 0, v108
	v_add_u32_e32 v117, 0, v110
	v_add_u32_e32 v118, 0, v112
	v_add_u32_e32 v131, s86, v58
	s_lshl_b32 s91, s3, 7
	v_mov_b32_e32 v82, 0xf149f2ca
	s_movk_i32 s93, 0xffe0
	s_add_i32 s92, 0, 0x20800
	v_mov_b32_e32 v132, 0xc000
	s_mov_b32 s94, 0xffff0000
	v_add_u32_e32 v133, v55, v53
	v_add_u32_e32 v134, v60, v56
	v_add_u32_e32 v135, v63, v62
	v_add_u32_e32 v136, v67, v87
	s_mov_b32 s95, 0xffff
	s_add_i32 s6, 0, 0x20804
	v_add_u32_e32 v138, v89, v54
	v_add_u32_e32 v139, v89, v59
	v_add_u32_e32 v140, v89, v84
	v_add_u32_e32 v141, v89, v88
	v_add_u32_e32 v142, v89, v90
	v_add_u32_e32 v143, v89, v91
	v_add_u32_e32 v144, v89, v92
	v_add_u32_e32 v145, v89, v93
	v_add_u32_e32 v146, v50, v51
	v_add_u32_e32 v147, v50, v86
	v_add_u32_e32 v148, v50, v94
	v_add_u32_e32 v149, v50, v52
	v_mbcnt_hi_u32_b32 v150, -1, v48
	v_mov_b32_e32 v48, 0
	v_mov_b32_e32 v49, v66
	v_mov_b32_e32 v50, v66
	v_mov_b32_e32 v51, v66
	v_mov_b32_e32 v52, 0
	v_mov_b32_e32 v53, v66
	v_mov_b32_e32 v54, v66
	v_mov_b32_e32 v55, v66
	v_mov_b32_e32 v56, 0
	v_mov_b32_e32 v57, v66
	v_mov_b32_e32 v58, v66
	v_mov_b32_e32 v59, v66
	v_mov_b32_e32 v60, 0
	v_mov_b32_e32 v61, v66
	v_mov_b32_e32 v62, v66
	v_mov_b32_e32 v63, v66
	s_waitcnt vmcnt(0)
	s_branch .LBB0_312

; #define GATE_LOAD(j) do { pg = *(const float2*)(scr + (j) * 384 + 2 * lane); pa = *(const float2*)(scr + (j) * 384 + 128 + 2 * lane); \
;         ppm = *(const float2*)(scr + (j) * 384 + 256 + 2 * lane); pG = scr[32 * 384 + (j)]; pPM = scr[32 * 384 + 32 + (j)]; } while (0)
; template <int SPLIT> __device__ __forceinline__ void scan_item(const Params& p, unsigned char* smem, const int item, const int vh) {
;     ...
;             if (wid == 0) {
;                 const float M127 = fmaxf(m_run, pPM);
;                 g_s[2 * lane] = pg.x; g_s[2 * lane + 1] = pg.y; a_s[2 * lane] = pa.x; a_s[2 * lane + 1] = pa.y;
;                 M_s[2 * lane] = fmaxf(m_run, ppm.x); M_s[2 * lane + 1] = fmaxf(m_run, ppm.y);
;                 if (lane == 0) { sc[0] = m_run; sc[1] = M127; }
;                 m_run = pG + M127;
;                 GATE_LOAD(jn);
;             }
.LBB0_312:
	s_add_i32 s0, s93, 33
	s_cmp_lg_u32 s93, -1
	v_readlane_b32 s4, v254, 54
	s_cselect_b32 vcc_lo, s0, 31
	v_readlane_b32 s5, v254, 55
	s_and_saveexec_b64 s[86:87], s[4:5]
	s_cbranch_execz .LBB0_316
	s_waitcnt vmcnt(16)
	v_max_f32_e32 v67, v83, v83
	v_max_f32_e32 v84, v82, v82
	v_max_f32_e32 v83, v84, v67
	v_max_f32_e32 v67, v70, v70
	v_max_f32_e32 v70, v84, v67
	v_max_f32_e32 v67, v71, v71
	v_max_f32_e32 v71, v84, v67
	ds_write_b64 v99, v[72:73]
	ds_write_b64 v100, v[74:75]
	ds_write_b64 v101, v[70:71]
	s_mov_b64 s[96:97], exec
	v_readlane_b32 s4, v254, 56
	v_readlane_b32 s5, v254, 57
	s_and_b64 s[4:5], s[96:97], s[4:5]
	s_mov_b64 exec, s[4:5]
	v_mov_b32_e32 v67, s92
	ds_write_b64 v67, v[82:83]
	s_or_b64 exec, exec, s[96:97]
	s_mov_b32 vcc_hi, s1
	s_mul_i32 s0, vcc_lo, 0x180
	s_lshl_b64 s[4:5], vcc, 2
	v_lshl_add_u64 v[70:71], s[0:1], 2, v[68:69]
	s_add_u32 s4, s84, s4
	v_add_f32_e32 v82, v97, v83
	s_addc_u32 s5, s85, s5
	global_load_dwordx2 v[72:73], v[70:71], off
	global_load_dwordx2 v[74:75], v[70:71], off offset:512
	s_nop 0
	global_load_dwordx2 v[70:71], v[70:71], off offset:1024
	s_nop 0
	global_load_dword v97, v132, s[4:5]
	global_load_dword v83, v132, s[4:5] offset:128

; __device__ void phase_attn(const Params& p, unsigned char* smem) {
;     ...
;     float gqm = 0.f, gkm = 0.f;
;     for (int i = 0; i < 128; ++i) { gqm = fmaxf(gqm, fabsf(p.qng[i])); gkm = fmaxf(gkm, fabsf(p.kng[i])); }
;     const float bound2 = (11.313708498984761f * 1.02f * gqm * gkm) * 1.4426950408889634f;
;     const float negBC = bound2 > 64.f ? 64.f - bound2 : 0.f;
.LBB0_476:
	s_cmp_lt_i32 s80, 6
	s_cselect_b64 s[0:1], -1, 0
	s_and_b64 s[4:5], s[0:1], s[4:5]
	s_andn2_b64 vcc, exec, s[4:5]
	s_cbranch_vccnz .LBB0_500
	v_readlane_b32 s8, v254, 16
	v_readlane_b32 s12, v254, 20
	v_readlane_b32 s13, v254, 21
	v_readlane_b32 s14, v254, 22
	v_readlane_b32 s15, v254, 23
	v_readlane_b32 s12, v254, 27
	v_readlane_b32 s14, v254, 29
	v_readlane_b32 s15, v254, 30
	v_readlane_b32 s26, v254, 41
	v_readlane_b32 s27, v254, 42
	s_mov_b64 s[4:5], 0
	s_waitcnt vmcnt(0)
	v_mov_b32_e32 v0, 0
	v_mov_b32_e32 v1, 0
	v_mov_b32_e32 v2, 0
	v_readlane_b32 s9, v254, 17
	s_mov_b64 s[14:15], s[26:27]
	v_readlane_b32 s10, v254, 18
	v_readlane_b32 s11, v254, 19
	v_readlane_b32 s13, v254, 28
	v_readlane_b32 s16, v254, 31
	v_readlane_b32 s17, v254, 32
	v_readlane_b32 s18, v254, 33
	v_readlane_b32 s19, v254, 34
	v_readlane_b32 s20, v254, 35
	v_readlane_b32 s21, v254, 36
	v_readlane_b32 s22, v254, 37
	v_readlane_b32 s23, v254, 38
	v_readlane_b32 s24, v254, 39
	v_readlane_b32 s25, v254, 40
	global_load_dwordx4 v[4:7], v0, s[14:15]
	global_load_dwordx4 v[8:11], v0, s[14:15] offset:16
	global_load_dwordx4 v[12:15], v0, s[14:15] offset:32
	global_load_dwordx4 v[16:19], v0, s[14:15] offset:48
	global_load_dwordx4 v[20:23], v0, s[14:15] offset:64
	global_load_dwordx4 v[24:27], v0, s[14:15] offset:80
	global_load_dwordx4 v[28:31], v0, s[14:15] offset:96
	global_load_dwordx4 v[32:35], v0, s[14:15] offset:112
	global_load_dwordx4 v[36:39], v0, s[14:15] offset:128
	global_load_dwordx4 v[40:43], v0, s[14:15] offset:144
	global_load_dwordx4 v[44:47], v0, s[14:15] offset:160
	global_load_dwordx4 v[48:51], v0, s[14:15] offset:176
	global_load_dwordx4 v[52:55], v0, s[14:15] offset:192
	global_load_dwordx4 v[56:59], v0, s[14:15] offset:208
	global_load_dwordx4 v[60:63], v0, s[14:15] offset:224
	global_load_dwordx4 v[64:67], v0, s[14:15] offset:240
	global_load_dwordx4 v[68:71], v0, s[14:15] offset:256
	global_load_dwordx4 v[72:75], v0, s[14:15] offset:272
	global_load_dwordx4 v[76:79], v0, s[14:15] offset:288
	global_load_dwordx4 v[80:83], v0, s[14:15] offset:304
	global_load_dwordx4 v[84:87], v0, s[14:15] offset:320
	global_load_dwordx4 v[88:91], v0, s[14:15] offset:336
	global_load_dwordx4 v[92:95], v0, s[14:15] offset:352
	global_load_dwordx4 v[96:99], v0, s[14:15] offset:368
	global_load_dwordx4 v[100:103], v0, s[14:15] offset:384
	global_load_dwordx4 v[104:107], v0, s[14:15] offset:400
	global_load_dwordx4 v[108:111], v0, s[14:15] offset:416
	global_load_dwordx4 v[112:115], v0, s[14:15] offset:432
	global_load_dwordx4 v[116:119], v0, s[14:15] offset:448
	global_load_dwordx4 v[120:123], v0, s[14:15] offset:464
	global_load_dwordx4 v[124:127], v0, s[14:15] offset:480
	global_load_dwordx4 v[128:131], v0, s[14:15] offset:496
	s_waitcnt vmcnt(0)
	v_max3_f32 v1, v1, |v4|, |v5|
	v_max3_f32 v1, v1, |v6|, |v7|
	v_max3_f32 v1, v1, |v8|, |v9|
	v_max3_f32 v1, v1, |v10|, |v11|
	v_max3_f32 v1, v1, |v12|, |v13|
	v_max3_f32 v1, v1, |v14|, |v15|
	v_max3_f32 v1, v1, |v16|, |v17|
	v_max3_f32 v1, v1, |v18|, |v19|
	v_max3_f32 v1, v1, |v20|, |v21|
	v_max3_f32 v1, v1, |v22|, |v23|
	v_max3_f32 v1, v1, |v24|, |v25|
	v_max3_f32 v1, v1, |v26|, |v27|
	v_max3_f32 v1, v1, |v28|, |v29|
	v_max3_f32 v1, v1, |v30|, |v31|
	v_max3_f32 v1, v1, |v32|, |v33|
	v_max3_f32 v1, v1, |v34|, |v35|
	v_max3_f32 v1, v1, |v36|, |v37|
	v_max3_f32 v1, v1, |v38|, |v39|
	v_max3_f32 v1, v1, |v40|, |v41|
	v_max3_f32 v1, v1, |v42|, |v43|
	v_max3_f32 v1, v1, |v44|, |v45|
	v_max3_f32 v1, v1, |v46|, |v47|
	v_max3_f32 v1, v1, |v48|, |v49|
	v_max3_f32 v1, v1, |v50|, |v51|
	v_max3_f32 v1, v1, |v52|, |v53|
	v_max3_f32 v1, v1, |v54|, |v55|
	v_max3_f32 v1, v1, |v56|, |v57|
	v_max3_f32 v1, v1, |v58|, |v59|
	v_max3_f32 v1, v1, |v60|, |v61|
	v_max3_f32 v1, v1, |v62|, |v63|
	v_max3_f32 v1, v1, |v64|, |v65|
	v_max3_f32 v1, v1, |v66|, |v67|
	v_max3_f32 v1, v1, |v68|, |v69|
	v_max3_f32 v1, v1, |v70|, |v71|
	v_max3_f32 v1, v1, |v72|, |v73|
	v_max3_f32 v1, v1, |v74|, |v75|
	v_max3_f32 v1, v1, |v76|, |v77|
	v_max3_f32 v1, v1, |v78|, |v79|
	v_max3_f32 v1, v1, |v80|, |v81|
	v_max3_f32 v1, v1, |v82|, |v83|
	v_max3_f32 v1, v1, |v84|, |v85|
	v_max3_f32 v1, v1, |v86|, |v87|
	v_max3_f32 v1, v1, |v88|, |v89|
	v_max3_f32 v1, v1, |v90|, |v91|
	v_max3_f32 v1, v1, |v92|, |v93|
	v_max3_f32 v1, v1, |v94|, |v95|
	v_max3_f32 v1, v1, |v96|, |v97|
	v_max3_f32 v1, v1, |v98|, |v99|
	v_max3_f32 v1, v1, |v100|, |v101|
	v_max3_f32 v1, v1, |v102|, |v103|
	v_max3_f32 v1, v1, |v104|, |v105|
	v_max3_f32 v1, v1, |v106|, |v107|
	v_max3_f32 v1, v1, |v108|, |v109|
	v_max3_f32 v1, v1, |v110|, |v111|
	v_max3_f32 v1, v1, |v112|, |v113|
	v_max3_f32 v1, v1, |v114|, |v115|
	v_max3_f32 v1, v1, |v116|, |v117|
	v_max3_f32 v1, v1, |v118|, |v119|
	v_max3_f32 v1, v1, |v120|, |v121|
	v_max3_f32 v1, v1, |v122|, |v123|
	v_max3_f32 v1, v1, |v124|, |v125|
	v_max3_f32 v1, v1, |v126|, |v127|
	v_max3_f32 v1, v1, |v128|, |v129|
	v_max3_f32 v1, v1, |v130|, |v131|
	global_load_dwordx4 v[4:7], v0, s[8:9]
	global_load_dwordx4 v[8:11], v0, s[8:9] offset:16
	global_load_dwordx4 v[12:15], v0, s[8:9] offset:32
	global_load_dwordx4 v[16:19], v0, s[8:9] offset:48
	global_load_dwordx4 v[20:23], v0, s[8:9] offset:64
	global_load_dwordx4 v[24:27], v0, s[8:9] offset:80
	global_load_dwordx4 v[28:31], v0, s[8:9] offset:96
	global_load_dwordx4 v[32:35], v0, s[8:9] offset:112
	global_load_dwordx4 v[36:39], v0, s[8:9] offset:128
	global_load_dwordx4 v[40:43], v0, s[8:9] offset:144
	global_load_dwordx4 v[44:47], v0, s[8:9] offset:160
	global_load_dwordx4 v[48:51], v0, s[8:9] offset:176
	global_load_dwordx4 v[52:55], v0, s[8:9] offset:192
	global_load_dwordx4 v[56:59], v0, s[8:9] offset:208
	global_load_dwordx4 v[60:63], v0, s[8:9] offset:224
	global_load_dwordx4 v[64:67], v0, s[8:9] offset:240
	global_load_dwordx4 v[68:71], v0, s[8:9] offset:256
	global_load_dwordx4 v[72:75], v0, s[8:9] offset:272
	global_load_dwordx4 v[76:79], v0, s[8:9] offset:288
	global_load_dwordx4 v[80:83], v0, s[8:9] offset:304
	global_load_dwordx4 v[84:87], v0, s[8:9] offset:320
	global_load_dwordx4 v[88:91], v0, s[8:9] offset:336
	global_load_dwordx4 v[92:95], v0, s[8:9] offset:352
	global_load_dwordx4 v[96:99], v0, s[8:9] offset:368
	global_load_dwordx4 v[100:103], v0, s[8:9] offset:384
	global_load_dwordx4 v[104:107], v0, s[8:9] offset:400
	global_load_dwordx4 v[108:111], v0, s[8:9] offset:416
	global_load_dwordx4 v[112:115], v0, s[8:9] offset:432
	global_load_dwordx4 v[116:119], v0, s[8:9] offset:448
	global_load_dwordx4 v[120:123], v0, s[8:9] offset:464
	global_load_dwordx4 v[124:127], v0, s[8:9] offset:480
	global_load_dwordx4 v[128:131], v0, s[8:9] offset:496
	s_waitcnt vmcnt(0)
; __device__ void phase_attn(const Params& p, unsigned char* smem) {
;     ...
;     for (int i = 0; i < 128; ++i) { gqm = fmaxf(gqm, fabsf(p.qng[i])); gkm = fmaxf(gkm, fabsf(p.kng[i])); }
;     const float bound2 = (11.313708498984761f * 1.02f * gqm * gkm) * 1.4426950408889634f;
;     const float negBC = bound2 > 64.f ? 64.f - bound2 : 0.f;
;     for (int slot_ = 0; slot_ < (REP_PH == 5 ? 16 : 8); ++slot_) { const int slot = slot_ & 7;
;         int pair, u, T, rb, hq, qb;
;         if (slot < 4) { pair = x + 8 * (slot >> 1); u = wl + 32 * (slot & 1); T = 4096; rb = (pair >> 1) * 4096; hq = u >> 4; qb = u & 15; }
;         else { pair = x + 8 * (slot - 4); u = wl; T = 2048; rb = NPROMPT + (pair >> 1) * 2048; hq = u >> 3; qb = u & 7; }
;         const int kvh = pair & 1, hg = kvh * 4 + hq; const size_t q0 = (size_t)rb + qb * 256;
	v_max3_f32 v2, v2, |v4|, |v5|
	v_max3_f32 v2, v2, |v6|, |v7|
	v_max3_f32 v2, v2, |v8|, |v9|
	v_max3_f32 v2, v2, |v10|, |v11|
	v_max3_f32 v2, v2, |v12|, |v13|
	v_max3_f32 v2, v2, |v14|, |v15|
	v_max3_f32 v2, v2, |v16|, |v17|
	v_max3_f32 v2, v2, |v18|, |v19|
	v_max3_f32 v2, v2, |v20|, |v21|
	v_max3_f32 v2, v2, |v22|, |v23|
	v_max3_f32 v2, v2, |v24|, |v25|
	v_max3_f32 v2, v2, |v26|, |v27|
	v_max3_f32 v2, v2, |v28|, |v29|
	v_max3_f32 v2, v2, |v30|, |v31|
	v_max3_f32 v2, v2, |v32|, |v33|
	v_max3_f32 v2, v2, |v34|, |v35|
	v_max3_f32 v2, v2, |v36|, |v37|
	v_max3_f32 v2, v2, |v38|, |v39|
	v_max3_f32 v2, v2, |v40|, |v41|
	v_max3_f32 v2, v2, |v42|, |v43|
	v_max3_f32 v2, v2, |v44|, |v45|
	v_max3_f32 v2, v2, |v46|, |v47|
	v_max3_f32 v2, v2, |v48|, |v49|
	v_max3_f32 v2, v2, |v50|, |v51|
	v_max3_f32 v2, v2, |v52|, |v53|
	v_max3_f32 v2, v2, |v54|, |v55|
	v_max3_f32 v2, v2, |v56|, |v57|
	v_max3_f32 v2, v2, |v58|, |v59|
	v_max3_f32 v2, v2, |v60|, |v61|
	v_max3_f32 v2, v2, |v62|, |v63|
	v_max3_f32 v2, v2, |v64|, |v65|
	v_max3_f32 v2, v2, |v66|, |v67|
	v_max3_f32 v2, v2, |v68|, |v69|
	v_max3_f32 v2, v2, |v70|, |v71|
	v_max3_f32 v2, v2, |v72|, |v73|
	v_max3_f32 v2, v2, |v74|, |v75|
	v_max3_f32 v2, v2, |v76|, |v77|
	v_max3_f32 v2, v2, |v78|, |v79|
	v_max3_f32 v2, v2, |v80|, |v81|
	v_max3_f32 v2, v2, |v82|, |v83|
	v_max3_f32 v2, v2, |v84|, |v85|
	v_max3_f32 v2, v2, |v86|, |v87|
	v_max3_f32 v2, v2, |v88|, |v89|
	v_max3_f32 v2, v2, |v90|, |v91|
	v_max3_f32 v2, v2, |v92|, |v93|
	v_max3_f32 v2, v2, |v94|, |v95|
	v_max3_f32 v2, v2, |v96|, |v97|
	v_max3_f32 v2, v2, |v98|, |v99|
	v_max3_f32 v2, v2, |v100|, |v101|
	v_max3_f32 v2, v2, |v102|, |v103|
	v_max3_f32 v2, v2, |v104|, |v105|
	v_max3_f32 v2, v2, |v106|, |v107|
	v_max3_f32 v2, v2, |v108|, |v109|
	v_max3_f32 v2, v2, |v110|, |v111|
	v_max3_f32 v2, v2, |v112|, |v113|
	v_max3_f32 v2, v2, |v114|, |v115|
	v_max3_f32 v2, v2, |v116|, |v117|
	v_max3_f32 v2, v2, |v118|, |v119|
	v_max3_f32 v2, v2, |v120|, |v121|
	v_max3_f32 v2, v2, |v122|, |v123|
	v_max3_f32 v2, v2, |v124|, |v125|
	v_max3_f32 v2, v2, |v126|, |v127|
	v_max3_f32 v2, v2, |v128|, |v129|
	v_max3_f32 v2, v2, |v130|, |v131|
	v_mul_f32_e32 v0, 0x4138a3c4, v1
	s_and_b32 s3, s2, 7
	v_mul_f32_e32 v0, v2, v0
	s_lshr_b32 s24, s2, 3
	v_mul_f32_e32 v1, 0x3fb8aa3b, v0
	v_mov_b32_e32 v2, 0x42800000
	s_or_b32 s26, s3, 0xffffffe0
	s_lshr_b32 s27, s2, 6
	s_bfe_u32 s28, s2, 0x30003
	s_bfe_u32 s29, s2, 0x40003
	v_cmp_gt_f32_e32 vcc, v1, v2
	v_fmac_f32_e32 v2, 0xbfb8aa3b, v0
	s_add_u32 s10, s78, 0x19cef600
	v_cndmask_b32_e32 v180, 0, v2, vcc
	s_addc_u32 s11, s79, 0
	v_mbcnt_hi_u32_b32 v177, -1, v193
	s_add_u32 s12, s78, 0x150a00
	v_and_b32_e32 v0, 64, v177
	v_cmp_neq_f32_e64 s[4:5], 0, v180
	s_mov_b32 s9, 0
	s_movk_i32 s25, 0xffe0
	v_mov_b32_e32 v182, v180
	v_mov_b32_e32 v183, v180
	s_addc_u32 s13, s79, 0
	s_movk_i32 s30, 0x1800
	v_mov_b32_e32 v185, 0
	s_movk_i32 s31, 0xc00
	v_xor_b32_e32 v179, 32, v177
	v_add_u32_e32 v195, 64, v0
	v_mov_b32_e32 v196, 0x358637bd
	s_mov_b32 s34, 0x800000
	v_cndmask_b32_e64 v197, 0, 1, s[4:5]
	s_mov_b32 s35, 0xfffd0000
	s_mov_b64 s[14:15], 0xc0000
	s_add_i32 s36, 0, 0x10000
	s_movk_i32 s37, 0x210
	s_mov_b32 s38, 0
	s_branch .LBB0_481
